# mixer-A dilated-group chunk loop: 22 redundant self-max canonicalisations folded into their consuming v_max (11 fewer VALU per chunk), otherwise identical to the previous best
# speedup vs baseline: 1.0025x; 1.0006x over previous
; __device__ __forceinline__ float xor32_max(float v) { auto rr = __builtin_amdgcn_permlane32_swap(__float_as_uint(v), __float_as_uint(v), false, false); return fmaxf(__uint_as_float(rr[0]), __uint_as_float(rr[1])); }
; __device__ __forceinline__ int crow(int r, int h) { return (r & 3) + 8 * (r >> 2) + 4 * h; }
; template <int MODE>
; __device__ __forceinline__ void soft_compute(SoftState& st, const bf16x8 (&qf)[4], const KV& t, int k0, int kst, int qp, int W, int dilm1, bool lane_ok, bool diag, const WaveCtx& c) {
;     store_v(t.vr, c);
;     VF vf; read_vf(vf, c);
;     f32x16 s = qk_ref(t.kf, qf, st.negm);
;     if (MODE == 0) {
;         const int relb = qp - k0;
;         const bool cls_ok = ((relb & dilm1) == 0);
; #pragma unroll
;         for (int r = 0; r < 16; ++r) {
;             const unsigned rel = (unsigned)(relb - kst * crow(r, c.h));
;             s[r] = (cls_ok && rel <= (unsigned)W) ? s[r] : -1e30f;
;         }
;     } else if (diag) {
; #pragma unroll
;         for (int r = 0; r < 16; ++r) { const int kp = k0 + crow(r, c.h); s[r] = (kp <= qp) ? s[r] : -1e30f; }
;     } else if (__ballot(!lane_ok) != 0ull) {
; #pragma unroll
;         for (int r = 0; r < 16; ++r) s[r] = lane_ok ? s[r] : -1e30f;
;     }
;     float mx = fmaxf(fmaxf(s[0], s[1]), fmaxf(s[2], s[3]));
; #pragma unroll
;     for (int r = 4; r < 16; r += 4) mx = fmaxf(mx, fmaxf(fmaxf(s[r], s[r + 1]), fmaxf(s[r + 2], s[r + 3])));
;     mx = xor32_max(mx);
;     if (__ballot(mx > 8.0f) != 0ull) {
;         const float d = fmaxf(mx, 0.f), scl = __builtin_amdgcn_exp2f(-d);
;         st.l *= scl; st.m += d;
;         const float nm = -st.m;
; #pragma unroll
;         for (int r = 0; r < 16; ++r) { st.o[0][r] *= scl; st.o[1][r] *= scl; s[r] -= d; st.negm[r] = nm; }
.LBB0_429:
	s_waitcnt vmcnt(0) lgkmcnt(0)
	v_mfma_f32_32x32x16_bf16 v[48:63], v[142:145], v[98:101], v[32:47]
	s_add_i32 s0, s25, -2
	s_cmp_lt_i32 s0, s8
	s_cselect_b32 s0, 0, s8
	s_cselect_b32 s1, s20, s21
	s_add_i32 s0, s0, s24
	s_lshl_b32 s0, s0, s22
	v_subrev_u32_e32 v64, s1, v172
	v_mfma_f32_32x32x16_bf16 v[48:63], v[134:137], v[102:105], v[48:63]
	v_add_u32_e32 v202, s0, v64
	v_and_b32_e32 v64, s23, v202
	v_cmp_eq_u32_e32 vcc, 0, v64
	v_sub_u32_e32 v64, v202, v165
	v_cmp_ge_u32_e64 s[0:1], s19, v64
	v_add_u32_e32 v203, v202, v195
	s_and_b64 s[0:1], vcc, s[0:1]
	v_mfma_f32_32x32x16_bf16 v[48:63], v[126:129], v[106:109], v[48:63]
	v_add_u32_e32 v248, v176, v196
	ds_write_b128 v248, v[138:141]
	ds_write_b128 v192, v[130:133]
	ds_write_b128 v193, v[118:121]
	ds_write_b128 v197, v[114:117]
	v_add_u32_e32 v247, s12, v215
	ds_read_b64_tr_b16 v[158:159], v247
	ds_read_b64_tr_b16 v[160:161], v247 offset:1152
	ds_read_b64_tr_b16 v[156:157], v247 offset:1216
	ds_read_b64_tr_b16 v[154:155], v247 offset:64
	ds_read_b64_tr_b16 v[150:151], v247 offset:2304
	ds_read_b64_tr_b16 v[152:153], v247 offset:3456
	ds_read_b64_tr_b16 v[148:149], v247 offset:3520
	ds_read_b64_tr_b16 v[146:147], v247 offset:2368
	v_mfma_f32_32x32x16_bf16 v[48:63], v[122:125], v[110:113], v[48:63]
	s_nop 11
	v_cndmask_b32_e64 v64, v244, v48, s[0:1]
	v_cmp_ge_u32_e64 s[0:1], s19, v203
	s_and_b64 s[0:1], vcc, s[0:1]
	v_sub_u32_e32 v48, v202, v218
	v_cndmask_b32_e64 v249, v244, v49, s[0:1]
	v_cmp_ge_u32_e64 s[0:1], s19, v48
	s_and_b64 s[0:1], vcc, s[0:1]
	v_sub_u32_e32 v48, v202, v219
	v_cndmask_b32_e64 v250, v244, v50, s[0:1]
	v_cmp_ge_u32_e64 s[0:1], s19, v48
	s_and_b64 s[0:1], vcc, s[0:1]
	v_sub_u32_e32 v48, v202, v220
	v_cndmask_b32_e64 v251, v244, v51, s[0:1]
	v_cmp_ge_u32_e64 s[0:1], s19, v48
	s_and_b64 s[0:1], vcc, s[0:1]
	v_sub_u32_e32 v48, v202, v221
	v_cndmask_b32_e64 v252, v244, v52, s[0:1]
	v_cmp_ge_u32_e64 s[0:1], s19, v48
	s_and_b64 s[0:1], vcc, s[0:1]
	v_sub_u32_e32 v48, v202, v222
	v_cndmask_b32_e64 v53, v244, v53, s[0:1]
	v_cmp_ge_u32_e64 s[0:1], s19, v48
	s_and_b64 s[0:1], vcc, s[0:1]
	v_sub_u32_e32 v48, v202, v223
	v_cndmask_b32_e64 v54, v244, v54, s[0:1]
	v_cmp_ge_u32_e64 s[0:1], s19, v48
	s_and_b64 s[0:1], vcc, s[0:1]
	v_sub_u32_e32 v48, v202, v224
	v_cndmask_b32_e64 v55, v244, v55, s[0:1]
	v_cmp_ge_u32_e64 s[0:1], s19, v48
	s_and_b64 s[0:1], vcc, s[0:1]
	v_sub_u32_e32 v48, v202, v225
	v_cndmask_b32_e64 v253, v244, v56, s[0:1]
	v_cmp_ge_u32_e64 s[0:1], s19, v48
	s_and_b64 s[0:1], vcc, s[0:1]
	v_sub_u32_e32 v48, v202, v226
	v_cndmask_b32_e64 v56, v244, v57, s[0:1]
	v_cmp_ge_u32_e64 s[0:1], s19, v48
	s_and_b64 s[0:1], vcc, s[0:1]
	v_sub_u32_e32 v48, v202, v227
	v_cndmask_b32_e64 v57, v244, v58, s[0:1]
	v_cmp_ge_u32_e64 s[0:1], s19, v48
	s_and_b64 s[0:1], vcc, s[0:1]
	v_sub_u32_e32 v49, v202, v228
	v_cndmask_b32_e64 v48, v244, v59, s[0:1]
	v_cmp_ge_u32_e64 s[0:1], s19, v49
	s_and_b64 s[0:1], vcc, s[0:1]
	v_sub_u32_e32 v50, v202, v229
	v_cndmask_b32_e64 v49, v244, v60, s[0:1]
	v_cmp_ge_u32_e64 s[0:1], s19, v50
	s_and_b64 s[0:1], vcc, s[0:1]
	v_sub_u32_e32 v50, v202, v230
	v_cndmask_b32_e64 v51, v244, v61, s[0:1]
	v_cmp_ge_u32_e64 s[0:1], s19, v50
	v_max_f32_e32 v58, v64, v249
	s_and_b64 s[0:1], vcc, s[0:1]
	v_sub_u32_e32 v52, v202, v231
	v_max_f32_e32 v59, v250, v251
	v_cndmask_b32_e64 v50, v244, v62, s[0:1]
	v_cmp_ge_u32_e64 s[0:1], s19, v52
	v_max_f32_e32 v60, v54, v55
	s_and_b64 vcc, vcc, s[0:1]
	v_max3_f32 v60, v252, v53, v60
	v_cndmask_b32_e32 v52, v244, v63, vcc
	v_max3_f32 v58, v58, v59, v60
	v_max_f32_e32 v59, v57, v48
	v_max_f32_e32 v61, v50, v50
	v_max_f32_e32 v60, v61, v52
	v_max3_f32 v59, v253, v56, v59
	v_max3_f32 v60, v49, v51, v60
	v_max3_f32 v58, v58, v59, v60
	v_mov_b32_e32 v59, v58
	s_nop 1
	v_permlane32_swap_b32_e32 v58, v59
	v_max_f32_e32 v59, v59, v59
	v_max_f32_e32 v58, v58, v59
	v_cmp_lt_f32_e32 vcc, s70, v58
	s_cbranch_vccz .LBB0_431
	v_max_f32_e32 v33, 0, v58
	v_exp_f32_e64 v34, -v33
	v_add_f32_e32 v171, v171, v33
	v_xor_b32_e32 v32, 0x80000000, v171
	v_sub_f32_e32 v64, v64, v33
	v_mul_f32_e32 v170, v170, v34
	v_sub_f32_e32 v249, v249, v33
	v_sub_f32_e32 v250, v250, v33
	v_sub_f32_e32 v251, v251, v33
	v_sub_f32_e32 v252, v252, v33
	v_sub_f32_e32 v53, v53, v33
	v_sub_f32_e32 v54, v54, v33
	v_sub_f32_e32 v55, v55, v33
	v_sub_f32_e32 v253, v253, v33
	v_sub_f32_e32 v56, v56, v33
	v_sub_f32_e32 v57, v57, v33
	v_sub_f32_e32 v48, v48, v33
	v_sub_f32_e32 v49, v49, v33
	v_sub_f32_e32 v51, v51, v33
	v_sub_f32_e32 v50, v50, v33
	v_pk_mul_f32 v[30:31], v[30:31], v[34:35] op_sel_hi:[1,0]
	v_pk_mul_f32 v[28:29], v[28:29], v[34:35] op_sel_hi:[1,0]
	v_pk_mul_f32 v[26:27], v[26:27], v[34:35] op_sel_hi:[1,0]
	v_pk_mul_f32 v[24:25], v[24:25], v[34:35] op_sel_hi:[1,0]
	v_pk_mul_f32 v[22:23], v[22:23], v[34:35] op_sel_hi:[1,0]
	v_pk_mul_f32 v[20:21], v[20:21], v[34:35] op_sel_hi:[1,0]
	v_pk_mul_f32 v[18:19], v[18:19], v[34:35] op_sel_hi:[1,0]
	v_pk_mul_f32 v[16:17], v[16:17], v[34:35] op_sel_hi:[1,0]
	v_pk_mul_f32 v[14:15], v[14:15], v[34:35] op_sel_hi:[1,0]
	v_pk_mul_f32 v[12:13], v[12:13], v[34:35] op_sel_hi:[1,0]
	v_pk_mul_f32 v[10:11], v[10:11], v[34:35] op_sel_hi:[1,0]
	v_pk_mul_f32 v[8:9], v[8:9], v[34:35] op_sel_hi:[1,0]
	v_pk_mul_f32 v[6:7], v[6:7], v[34:35] op_sel_hi:[1,0]
	v_pk_mul_f32 v[4:5], v[4:5], v[34:35] op_sel_hi:[1,0]
	v_pk_mul_f32 v[2:3], v[2:3], v[34:35] op_sel_hi:[1,0]
	v_pk_mul_f32 v[0:1], v[0:1], v[34:35] op_sel_hi:[1,0]
	v_sub_f32_e32 v52, v52, v33
	v_mov_b32_e32 v33, v32
	v_mov_b32_e32 v34, v32
	v_mov_b32_e32 v35, v32
	v_mov_b32_e32 v36, v32
	v_mov_b32_e32 v37, v32
	v_mov_b32_e32 v38, v32
	v_mov_b32_e32 v39, v32
	v_mov_b32_e32 v40, v32
	v_mov_b32_e32 v41, v32
	v_mov_b32_e32 v42, v32
	v_mov_b32_e32 v43, v32
	v_mov_b32_e32 v44, v32
	v_mov_b32_e32 v45, v32
	v_mov_b32_e32 v46, v32
	v_mov_b32_e32 v47, v32

; __device__ __forceinline__ float xor32_max(float v) { auto rr = __builtin_amdgcn_permlane32_swap(__float_as_uint(v), __float_as_uint(v), false, false); return fmaxf(__uint_as_float(rr[0]), __uint_as_float(rr[1])); }
; __device__ __forceinline__ int crow(int r, int h) { return (r & 3) + 8 * (r >> 2) + 4 * h; }
; template <int MODE>
; __device__ __forceinline__ void soft_compute(SoftState& st, const bf16x8 (&qf)[4], const KV& t, int k0, int kst, int qp, int W, int dilm1, bool lane_ok, bool diag, const WaveCtx& c) {
;     store_v(t.vr, c);
;     VF vf; read_vf(vf, c);
;     f32x16 s = qk_ref(t.kf, qf, st.negm);
;     if (MODE == 0) {
;         const int relb = qp - k0;
;         const bool cls_ok = ((relb & dilm1) == 0);
; #pragma unroll
;         for (int r = 0; r < 16; ++r) {
;             const unsigned rel = (unsigned)(relb - kst * crow(r, c.h));
;             s[r] = (cls_ok && rel <= (unsigned)W) ? s[r] : -1e30f;
;         }
;     } else if (diag) {
; #pragma unroll
;         for (int r = 0; r < 16; ++r) { const int kp = k0 + crow(r, c.h); s[r] = (kp <= qp) ? s[r] : -1e30f; }
;     } else if (__ballot(!lane_ok) != 0ull) {
; #pragma unroll
;         for (int r = 0; r < 16; ++r) s[r] = lane_ok ? s[r] : -1e30f;
;     }
;     float mx = fmaxf(fmaxf(s[0], s[1]), fmaxf(s[2], s[3]));
; #pragma unroll
;     for (int r = 4; r < 16; r += 4) mx = fmaxf(mx, fmaxf(fmaxf(s[r], s[r + 1]), fmaxf(s[r + 2], s[r + 3])));
;     mx = xor32_max(mx);
;     if (__ballot(mx > 8.0f) != 0ull) {
;         const float d = fmaxf(mx, 0.f), scl = __builtin_amdgcn_exp2f(-d);
;         st.l *= scl; st.m += d;
;         const float nm = -st.m;
; #pragma unroll
;         for (int r = 0; r < 16; ++r) { st.o[0][r] *= scl; st.o[1][r] *= scl; s[r] -= d; st.negm[r] = nm; }
.LBB0_434:
	v_mfma_f32_32x32x16_bf16 v[48:63], v[66:69], v[98:101], v[32:47]
	s_cmp_lt_i32 s26, s8
	s_cselect_b32 s0, 0, s8
	s_cselect_b32 s1, s20, s21
	s_add_i32 s0, s0, s24
	s_add_i32 s0, s0, -1
	s_lshl_b32 s0, s0, s22
	v_subrev_u32_e32 v64, s1, v172
	v_mfma_f32_32x32x16_bf16 v[48:63], v[70:73], v[102:105], v[48:63]
	v_add_u32_e32 v202, s0, v64
	v_and_b32_e32 v64, s23, v202
	v_cmp_eq_u32_e32 vcc, 0, v64
	v_sub_u32_e32 v64, v202, v165
	v_cmp_ge_u32_e64 s[0:1], s19, v64
	s_and_b64 s[0:1], vcc, s[0:1]
	ds_write_b128 v248, v[82:85]
	ds_write_b128 v192, v[86:89]
	ds_write_b128 v193, v[90:93]
	ds_write_b128 v197, v[94:97]
	v_mfma_f32_32x32x16_bf16 v[48:63], v[74:77], v[106:109], v[48:63]
	ds_read_b64_tr_b16 v[158:159], v247
	ds_read_b64_tr_b16 v[160:161], v247 offset:1152
	ds_read_b64_tr_b16 v[150:151], v247 offset:2304
	ds_read_b64_tr_b16 v[152:153], v247 offset:3456
	ds_read_b64_tr_b16 v[154:155], v247 offset:64
	ds_read_b64_tr_b16 v[156:157], v247 offset:1216
	ds_read_b64_tr_b16 v[146:147], v247 offset:2368
	ds_read_b64_tr_b16 v[148:149], v247 offset:3520
	v_mfma_f32_32x32x16_bf16 v[48:63], v[78:81], v[110:113], v[48:63]
	s_nop 11
	v_cndmask_b32_e64 v64, v244, v48, s[0:1]
	v_add_u32_e32 v48, v202, v195
	v_cmp_ge_u32_e64 s[0:1], s19, v48
	s_and_b64 s[0:1], vcc, s[0:1]
	v_sub_u32_e32 v48, v202, v218
	v_cndmask_b32_e64 v247, v244, v49, s[0:1]
	v_cmp_ge_u32_e64 s[0:1], s19, v48
	s_and_b64 s[0:1], vcc, s[0:1]
	v_sub_u32_e32 v48, v202, v219
	v_cndmask_b32_e64 v248, v244, v50, s[0:1]
	v_cmp_ge_u32_e64 s[0:1], s19, v48
	s_and_b64 s[0:1], vcc, s[0:1]
	v_sub_u32_e32 v48, v202, v220
	v_cndmask_b32_e64 v249, v244, v51, s[0:1]
	v_cmp_ge_u32_e64 s[0:1], s19, v48
	s_and_b64 s[0:1], vcc, s[0:1]
	v_sub_u32_e32 v48, v202, v221
	v_cndmask_b32_e64 v250, v244, v52, s[0:1]
	v_cmp_ge_u32_e64 s[0:1], s19, v48
	s_and_b64 s[0:1], vcc, s[0:1]
	v_sub_u32_e32 v48, v202, v222
	v_cndmask_b32_e64 v53, v244, v53, s[0:1]
	v_cmp_ge_u32_e64 s[0:1], s19, v48
	s_and_b64 s[0:1], vcc, s[0:1]
	v_sub_u32_e32 v48, v202, v223
	v_cndmask_b32_e64 v54, v244, v54, s[0:1]
	v_cmp_ge_u32_e64 s[0:1], s19, v48
	s_and_b64 s[0:1], vcc, s[0:1]
	v_sub_u32_e32 v48, v202, v224
	v_cndmask_b32_e64 v55, v244, v55, s[0:1]
	v_cmp_ge_u32_e64 s[0:1], s19, v48
	s_and_b64 s[0:1], vcc, s[0:1]
	v_sub_u32_e32 v48, v202, v225
	v_cndmask_b32_e64 v251, v244, v56, s[0:1]
	v_cmp_ge_u32_e64 s[0:1], s19, v48
	s_and_b64 s[0:1], vcc, s[0:1]
	v_sub_u32_e32 v48, v202, v226
	v_cndmask_b32_e64 v56, v244, v57, s[0:1]
	v_cmp_ge_u32_e64 s[0:1], s19, v48
	s_and_b64 s[0:1], vcc, s[0:1]
	v_sub_u32_e32 v48, v202, v227
	v_cndmask_b32_e64 v57, v244, v58, s[0:1]
	v_cmp_ge_u32_e64 s[0:1], s19, v48
	s_and_b64 s[0:1], vcc, s[0:1]
	v_sub_u32_e32 v49, v202, v228
	v_cndmask_b32_e64 v48, v244, v59, s[0:1]
	v_cmp_ge_u32_e64 s[0:1], s19, v49
	s_and_b64 s[0:1], vcc, s[0:1]
	v_sub_u32_e32 v50, v202, v229
	v_cndmask_b32_e64 v49, v244, v60, s[0:1]
	v_cmp_ge_u32_e64 s[0:1], s19, v50
	s_and_b64 s[0:1], vcc, s[0:1]
	v_sub_u32_e32 v50, v202, v230
	v_cndmask_b32_e64 v51, v244, v61, s[0:1]
	v_cmp_ge_u32_e64 s[0:1], s19, v50
	v_max_f32_e32 v58, v64, v247
	s_and_b64 s[0:1], vcc, s[0:1]
	v_sub_u32_e32 v52, v202, v231
	v_max_f32_e32 v59, v248, v249
	v_cndmask_b32_e64 v50, v244, v62, s[0:1]
	v_cmp_ge_u32_e64 s[0:1], s19, v52
	v_max_f32_e32 v60, v54, v55
	s_and_b64 vcc, vcc, s[0:1]
	v_max3_f32 v60, v250, v53, v60
	v_cndmask_b32_e32 v52, v244, v63, vcc
	v_max3_f32 v58, v58, v59, v60
	v_max_f32_e32 v59, v57, v48
	v_max_f32_e32 v61, v50, v50
	v_max_f32_e32 v60, v61, v52
	v_max3_f32 v59, v251, v56, v59
	v_max3_f32 v60, v49, v51, v60
	v_max3_f32 v58, v58, v59, v60
	v_mov_b32_e32 v59, v58
	s_nop 1
	v_permlane32_swap_b32_e32 v58, v59
	v_max_f32_e32 v59, v59, v59
	v_max_f32_e32 v58, v58, v59
	v_cmp_lt_f32_e32 vcc, s70, v58
	s_cbranch_vccz .LBB0_436
	v_max_f32_e32 v33, 0, v58
	v_exp_f32_e64 v34, -v33
	v_add_f32_e32 v171, v171, v33
	v_xor_b32_e32 v32, 0x80000000, v171
	v_sub_f32_e32 v64, v64, v33
	v_mul_f32_e32 v170, v170, v34
	v_sub_f32_e32 v247, v247, v33
	v_sub_f32_e32 v248, v248, v33
	v_sub_f32_e32 v249, v249, v33
	v_sub_f32_e32 v250, v250, v33
	v_sub_f32_e32 v53, v53, v33
	v_sub_f32_e32 v54, v54, v33
	v_sub_f32_e32 v55, v55, v33
	v_sub_f32_e32 v251, v251, v33
	v_sub_f32_e32 v56, v56, v33
	v_sub_f32_e32 v57, v57, v33
	v_sub_f32_e32 v48, v48, v33
	v_sub_f32_e32 v49, v49, v33
	v_sub_f32_e32 v51, v51, v33
	v_sub_f32_e32 v50, v50, v33
	v_pk_mul_f32 v[30:31], v[30:31], v[34:35] op_sel_hi:[1,0]
	v_pk_mul_f32 v[28:29], v[28:29], v[34:35] op_sel_hi:[1,0]
	v_pk_mul_f32 v[26:27], v[26:27], v[34:35] op_sel_hi:[1,0]
	v_pk_mul_f32 v[24:25], v[24:25], v[34:35] op_sel_hi:[1,0]
	v_pk_mul_f32 v[22:23], v[22:23], v[34:35] op_sel_hi:[1,0]
	v_pk_mul_f32 v[20:21], v[20:21], v[34:35] op_sel_hi:[1,0]
	v_pk_mul_f32 v[18:19], v[18:19], v[34:35] op_sel_hi:[1,0]
	v_pk_mul_f32 v[16:17], v[16:17], v[34:35] op_sel_hi:[1,0]
	v_pk_mul_f32 v[14:15], v[14:15], v[34:35] op_sel_hi:[1,0]
	v_pk_mul_f32 v[12:13], v[12:13], v[34:35] op_sel_hi:[1,0]
	v_pk_mul_f32 v[10:11], v[10:11], v[34:35] op_sel_hi:[1,0]
	v_pk_mul_f32 v[8:9], v[8:9], v[34:35] op_sel_hi:[1,0]
	v_pk_mul_f32 v[6:7], v[6:7], v[34:35] op_sel_hi:[1,0]
	v_pk_mul_f32 v[4:5], v[4:5], v[34:35] op_sel_hi:[1,0]
	v_pk_mul_f32 v[2:3], v[2:3], v[34:35] op_sel_hi:[1,0]
	v_pk_mul_f32 v[0:1], v[0:1], v[34:35] op_sel_hi:[1,0]
	v_sub_f32_e32 v52, v52, v33
	v_mov_b32_e32 v33, v32
	v_mov_b32_e32 v34, v32
	v_mov_b32_e32 v35, v32
	v_mov_b32_e32 v36, v32
	v_mov_b32_e32 v37, v32
	v_mov_b32_e32 v38, v32
	v_mov_b32_e32 v39, v32
	v_mov_b32_e32 v40, v32
	v_mov_b32_e32 v41, v32
	v_mov_b32_e32 v42, v32
	v_mov_b32_e32 v43, v32
	v_mov_b32_e32 v44, v32
	v_mov_b32_e32 v45, v32
	v_mov_b32_e32 v46, v32
	v_mov_b32_e32 v47, v32
